# v42 + attention loop: the two V-tile LDS-DMA issues spread to behind MFMAs 4 and 7
# speedup vs baseline: 1.0070x; 1.0062x over previous
; #define SB() __builtin_amdgcn_sched_barrier(0)
; #define MF32(a,b,c) __builtin_amdgcn_mfma_f32_32x32x16_bf16(a,b,c,0,0,0)
; #define EXP1(x) x=__builtin_amdgcn_exp2f((x)-mh_)
; __device__ __forceinline__ bf16x8 vfrag(lds_cptr vp,int i){ const s16x4 lo=vtr(vp+(i&3)*4096+(i>>2)*1024), hh=vtr(vp+(i&3)*4096+(i>>2)*1024+512); return (bf16x8){lo[0],lo[1],lo[2],lo[3],hh[0],hh[1],hh[2],hh[3]}; }
; __device__ __forceinline__ u32x4 packw(const f32x16&p,int base){ u32x4 w; w[0]=cvtpk_s(p[base],p[base+1]); w[1]=cvtpk_s(p[base+2],p[base+3]); w[2]=cvtpk_s(p[base+4],p[base+5]); w[3]=cvtpk_s(p[base+6],p[base+7]); return w; }
;   #define KF(i) LDSQ(kpn+((i)>>1)*2048+((i)&1)*512)
;   #define QF(d0) LDSQ(qp+(d0)*1024)
; template<int THRL,bool FIRST> __device__ __forceinline__ void step_main(f32x16&p0,f32x16&p1,f32x16&n0,f32x16&n1,St&S,lds_cptr kpn,lds_cptr qp,lds_cptr vp,float*wsf,int r32,int hi,float&rm){
;     ...
;   bf16x8 ka=KF(0),kb=KF(1),kc=KF(2),kd=KF(3),qa=QF(0),qb=QF(1);
;   decide<THRL,FIRST>(rm,S,wsf,r32,hi);
;   u32x4 pw0,pw1,pw2,pw3; const float mh_=S.mhat; const f32x16 z=f32x16{};
;   SB();
;   n0=MF32(ka,qa,z); ka=KF(4); EXP1(p0[0]);EXP1(p0[1]);EXP1(p0[2]); SB();
;   n1=MF32(kb,qa,z); kb=KF(5); qa=QF(2); EXP1(p0[3]);EXP1(p0[4]);EXP1(p0[5]); SB();
;   n0=MF32(kc,qb,n0);   kc=KF(6); EXP1(p0[6]);EXP1(p0[7]);EXP1(p0[8]); SB();
;   n1=MF32(kd,qb,n1);   kd=KF(7); qb=QF(3); EXP1(p0[9]);EXP1(p0[10]);EXP1(p0[11]); SB();
;   bf16x8 vfa=vfrag(vp,0);
;   n0=MF32(ka,qa,n0);   EXP1(p0[12]);EXP1(p0[13]);EXP1(p0[14]); pw0=packw(p0,0); SB();
;   bf16x8 vfb=vfrag(vp,1);
;   n1=MF32(kb,qa,n1);   EXP1(p0[15]);EXP1(p1[0]);EXP1(p1[1]); SB();
;   bf16x8 vfc=vfrag(vp,2);
;   n0=MF32(kc,qb,n0);   EXP1(p1[2]);EXP1(p1[3]);EXP1(p1[4]); pw1=packw(p0,8); SB();
;   bf16x8 vfd=vfrag(vp,3);
;   n1=MF32(kd,qb,n1);   EXP1(p1[5]);EXP1(p1[6]);EXP1(p1[7]); SB();
.LBB0_277:
	s_add_i32 s4, s91, 0x2000
	s_cmpk_lg_i32 s91, 0x4000
	s_cselect_b32 s88, s4, 0
	s_add_i32 s90, s90, 2
	v_mfma_f32_32x32x16_bf16 v[98:113], v[204:207], v[164:167], v[146:161]
	s_add_i32 s4, s88, s84
	s_add_u32 s60, s58, 0xc0000
	s_addc_u32 s61, s59, 0
	s_mov_b32 s5, m0
	s_mov_b32 m0, s4
	s_nop 0
	global_load_lds_dwordx4 v252, s[60:61]
	s_mov_b32 m0, s5
	v_exp_f32_e32 v130, v130
	v_exp_f32_e32 v131, v131
	v_exp_f32_e32 v132, v132
	v_exp_f32_e32 v133, v133
	v_exp_f32_e32 v134, v134
	v_exp_f32_e32 v135, v135
	v_mfma_f32_32x32x16_bf16 v[82:97], v[208:211], v[164:167], v[146:161]
	v_mfma_f32_32x32x16_bf16 v[98:113], v[212:215], v[168:171], v[98:113]
	v_exp_f32_e32 v136, v136
	v_exp_f32_e32 v137, v137
	v_exp_f32_e32 v138, v138
	v_mfma_f32_32x32x16_bf16 v[82:97], v[216:219], v[168:171], v[82:97]
	s_add_u32 s60, s50, 0xc0000
	s_addc_u32 s61, s51, 0
	s_mov_b32 s4, m0
	s_mov_b32 m0, s80
	s_nop 0
	global_load_lds_dwordx4 v250, s[60:61]
	s_mov_b32 m0, s4
	v_exp_f32_e32 v139, v139
	v_exp_f32_e32 v140, v140
	v_exp_f32_e32 v141, v141
	v_mfma_f32_32x32x16_bf16 v[98:113], v[220:223], v[172:175], v[98:113]
	v_exp_f32_e32 v142, v142
	ds_read_b64_tr_b16 v[4:5], v246 offset:40960
	ds_read_b64_tr_b16 v[6:7], v246 offset:41472
	v_exp_f32_e32 v143, v143
	v_exp_f32_e32 v144, v144
	v_cvt_pk_bf16_f32 v8, v130, v131
	v_cvt_pk_bf16_f32 v9, v132, v133
	v_cvt_pk_bf16_f32 v10, v134, v135
	v_cvt_pk_bf16_f32 v11, v136, v137
	v_mfma_f32_32x32x16_bf16 v[82:97], v[224:227], v[172:175], v[82:97]
	ds_read_b64_tr_b16 v[178:179], v246 offset:45056
	ds_read_b64_tr_b16 v[180:181], v246 offset:45568
	v_exp_f32_e32 v145, v145
	v_exp_f32_e32 v114, v114
	v_exp_f32_e32 v115, v115
	v_mfma_f32_32x32x16_bf16 v[98:113], v[228:231], v[236:239], v[98:113]
	ds_read_b64_tr_b16 v[182:183], v246 offset:49152
	ds_read_b64_tr_b16 v[184:185], v246 offset:49664
	s_add_u32 s60, s50, 0xc0080
	s_addc_u32 s61, s51, 0
	s_mov_b32 s4, m0
	s_mov_b32 m0, s83
	s_nop 0
	global_load_lds_dwordx4 v250, s[60:61]
	s_mov_b32 m0, s4
	v_exp_f32_e32 v116, v116
	v_exp_f32_e32 v117, v117
	v_exp_f32_e32 v118, v118
	v_cvt_pk_bf16_f32 v186, v138, v139
	v_cvt_pk_bf16_f32 v187, v140, v141
	v_cvt_pk_bf16_f32 v188, v142, v143
	v_cvt_pk_bf16_f32 v189, v144, v145
	v_mfma_f32_32x32x16_bf16 v[82:97], v[232:235], v[236:239], v[82:97]
	v_add_u32_e32 v240, s91, v249
	ds_read_b64_tr_b16 v[190:191], v246 offset:53248
	ds_read_b64_tr_b16 v[192:193], v246 offset:53760
	v_exp_f32_e32 v119, v119
	v_exp_f32_e32 v120, v120
	v_exp_f32_e32 v121, v121
	s_waitcnt lgkmcnt(6)
	v_mfma_f32_32x32x16_bf16 v[18:33], v[8:11], v[4:7], v[18:33]
	ds_read_b64_tr_b16 v[12:13], v246 offset:41984
	ds_read_b64_tr_b16 v[14:15], v246 offset:42496
	ds_read_b128 v[204:207], v240
	v_add_f32_e32 v194, v130, v131
	v_exp_f32_e32 v122, v122
	v_exp_f32_e32 v123, v123
	v_add_f32_e32 v194, v132, v194
	v_add_f32_e32 v4, v133, v194
	v_add_f32_e32 v4, v134, v4
	v_add_f32_e32 v194, v135, v4
	s_waitcnt lgkmcnt(7)
	v_mfma_f32_32x32x16_bf16 v[34:49], v[8:11], v[178:181], v[34:49]
	ds_read_b64_tr_b16 v[4:5], v246 offset:46080
	ds_read_b64_tr_b16 v[6:7], v246 offset:46592
	ds_read_b128 v[208:211], v240 offset:512
	v_exp_f32_e32 v124, v124
	v_exp_f32_e32 v125, v125
	v_add_f32_e32 v194, v136, v194
	v_add_f32_e32 v178, v137, v194
	v_add_f32_e32 v178, v138, v178
	v_add_f32_e32 v194, v139, v178
	s_waitcnt lgkmcnt(8)
	v_mfma_f32_32x32x16_bf16 v[50:65], v[8:11], v[182:185], v[50:65]
	ds_read_b64_tr_b16 v[178:179], v246 offset:50176
	ds_read_b64_tr_b16 v[180:181], v246 offset:50688
	ds_read_b128 v[212:215], v240 offset:2048
	v_exp_f32_e32 v126, v126
	v_exp_f32_e32 v127, v127
	v_add_f32_e32 v194, v140, v194
	v_add_f32_e32 v182, v141, v194
	v_add_f32_e32 v182, v142, v182
	v_add_f32_e32 v194, v143, v182
	s_waitcnt lgkmcnt(9)
; __device__ __forceinline__ float max3f(float a,float b,float c){float r;asm("v_max3_f32 %0, %1, %2, %3":"=v"(r):"v"(a),"v"(b),"v"(c));return r;}
; __device__ __forceinline__ float max2f(float a,float b){float r;asm("v_max_f32_e32 %0, %1, %2":"=v"(r):"v"(a),"v"(b));return r;}
; #define EXP1(x) x=__builtin_amdgcn_exp2f((x)-mh_)
;   #define PINAB() asm volatile("":"+v"(ma),"+v"(mb))
; template<int THRL,bool FIRST> __device__ __forceinline__ void step_main(f32x16&p0,f32x16&p1,f32x16&n0,f32x16&n1,St&S,lds_cptr kpn,lds_cptr qp,lds_cptr vp,float*wsf,int r32,int hi,float&rm){
;     ...
;   PVG(0,pw0,vfa,4, p0[2],p0[3],p0[4],p0[5],   do{EXP1(p1[8]);EXP1(p1[9]);}while(0));
;   PVG(1,pw0,vfb,5, p0[6],p0[7],p0[8],p0[9], do{EXP1(p1[10]);EXP1(p1[11]);}while(0));
;   PVG(2,pw0,vfc,6, p0[10],p0[11],p0[12],p0[13], do{EXP1(p1[12]);EXP1(p1[13]);}while(0));
;   PVG(3,pw0,vfd,7, p0[14],p0[15],p1[0],p1[1],   do{EXP1(p1[14]);EXP1(p1[15]);}while(0));
;   PVG(4,pw1,vfa,8, p1[2],p1[3],p1[4],p1[5],   pw2=packw(p1,0));
;   PVG(5,pw1,vfb,9, p1[6],p1[7],p1[8],p1[9], pw3=packw(p1,8));
;   PVG(6,pw1,vfc,10, p1[10],p1[11],p1[12],p1[13], do{}while(0));
;   PVG(7,pw1,vfd,11, p1[14],p1[15],0.f,0.f, do{}while(0));
;   float ma,mb;
;     ...
;   PVG(8,pw2,vfa,12,0.f,0.f,0.f,0.f, do{ma=max3f(n0[0],n0[1],n1[0]);mb=max3f(n0[2],n0[3],n1[1]);PINAB();}while(0));
;   PVG(9,pw2,vfb,13,0.f,0.f,0.f,0.f, do{ma=max3f(ma,n1[2],n1[3]);mb=max3f(mb,n0[4],n0[5]);PINAB();}while(0));
;   PVG(10,pw2,vfc,14,0.f,0.f,0.f,0.f, do{ma=max3f(ma,n0[6],n0[7]);mb=max3f(mb,n1[4],n1[5]);PINAB();}while(0));
;   PVG(11,pw2,vfd,15,0.f,0.f,0.f,0.f, do{ma=max3f(ma,n1[6],n1[7]);mb=max3f(mb,n0[8],n0[9]);PINAB();}while(0));
;   PVG(12,pw3,vfa,16,0.f,0.f,0.f,0.f, do{ma=max3f(ma,n0[10],n0[11]);mb=max3f(mb,n1[8],n1[9]);PINAB();}while(0));
;   PVG(13,pw3,vfb,16,0.f,0.f,0.f,0.f, do{ma=max3f(ma,n1[10],n1[11]);mb=max3f(mb,n0[12],n0[13]);PINAB();}while(0));
;   PVG(14,pw3,vfc,16,0.f,0.f,0.f,0.f, do{ma=max3f(ma,n0[14],n0[15]);mb=max3f(mb,n1[12],n1[13]);PINAB();}while(0));
;   PVG(15,pw3,vfd,16,0.f,0.f,0.f,0.f, do{ma=max3f(ma,n1[14],n1[15]);ma=max2f(ma,mb);PINAB();}while(0));
;     ...
;   { auto rr=__builtin_amdgcn_permlane32_swap(__float_as_uint(ma),__float_as_uint(ma),false,false); rm=max2f(__uint_as_float(rr[0]),__uint_as_float(rr[1])); }
	v_mfma_f32_32x32x16_bf16 v[66:81], v[8:11], v[190:193], v[66:81]
	ds_read_b64_tr_b16 v[182:183], v246 offset:54272
	ds_read_b64_tr_b16 v[184:185], v246 offset:54784
	ds_read_b128 v[216:219], v240 offset:2560
	v_exp_f32_e32 v128, v128
	v_exp_f32_e32 v129, v129
	v_add_f32_e32 v194, v144, v194
	v_add_f32_e32 v8, v145, v194
	v_add_f32_e32 v8, v114, v8
	v_add_f32_e32 v190, v115, v8
	s_waitcnt lgkmcnt(10)
	v_mfma_f32_32x32x16_bf16 v[18:33], v[186:189], v[12:15], v[18:33]
	ds_read_b64_tr_b16 v[8:9], v246 offset:43008
	ds_read_b64_tr_b16 v[10:11], v246 offset:43520
	ds_read_b128 v[220:223], v240 offset:4096
	v_add_f32_e32 v190, v116, v190
	v_add_f32_e32 v190, v117, v190
	v_add_f32_e32 v190, v118, v190
	v_add_f32_e32 v194, v119, v190
	v_cvt_pk_bf16_f32 v12, v114, v115
	v_cvt_pk_bf16_f32 v13, v116, v117
	v_cvt_pk_bf16_f32 v14, v118, v119
	v_cvt_pk_bf16_f32 v15, v120, v121
	s_waitcnt lgkmcnt(10)
	v_mfma_f32_32x32x16_bf16 v[34:49], v[186:189], v[4:7], v[34:49]
	ds_read_b64_tr_b16 v[190:191], v246 offset:47104
	ds_read_b64_tr_b16 v[192:193], v246 offset:47616
	ds_read_b128 v[224:227], v240 offset:4608
	v_add_f32_e32 v194, v120, v194
	v_add_f32_e32 v194, v121, v194
	v_add_f32_e32 v194, v122, v194
	v_add_f32_e32 v198, v123, v194
	v_cvt_pk_bf16_f32 v4, v122, v123
	v_cvt_pk_bf16_f32 v5, v124, v125
	v_cvt_pk_bf16_f32 v6, v126, v127
	v_cvt_pk_bf16_f32 v7, v128, v129
	s_waitcnt lgkmcnt(10)
	v_mfma_f32_32x32x16_bf16 v[50:65], v[186:189], v[178:181], v[50:65]
	ds_read_b64_tr_b16 v[194:195], v246 offset:51200
	ds_read_b64_tr_b16 v[196:197], v246 offset:51712
	ds_read_b128 v[228:231], v240 offset:6144
	v_add_f32_e32 v198, v124, v198
	v_add_f32_e32 v198, v125, v198
	v_add_f32_e32 v198, v126, v198
	v_add_f32_e32 v198, v127, v198
	s_waitcnt lgkmcnt(10)
	v_mfma_f32_32x32x16_bf16 v[66:81], v[186:189], v[182:185], v[66:81]
	ds_read_b64_tr_b16 v[178:179], v246 offset:55296
	ds_read_b64_tr_b16 v[180:181], v246 offset:55808
	ds_read_b128 v[232:235], v240 offset:6656
	v_add_f32_e32 v198, v128, v198
	v_add_f32_e32 v198, v129, v198
	v_add_f32_e32 v198, 0, v198
	s_waitcnt lgkmcnt(10)
	v_mfma_f32_32x32x16_bf16 v[18:33], v[12:15], v[8:11], v[18:33]
	ds_read_b64_tr_b16 v[182:183], v246 offset:44032
	ds_read_b64_tr_b16 v[184:185], v246 offset:44544
	v_max3_f32 v186, v98, v99, v82
	v_max3_f32 v187, v100, v101, v83
	s_nop 0
	s_waitcnt lgkmcnt(9)
	v_mfma_f32_32x32x16_bf16 v[34:49], v[12:15], v[190:193], v[34:49]
	ds_read_b64_tr_b16 v[8:9], v246 offset:48128
	ds_read_b64_tr_b16 v[10:11], v246 offset:48640
	v_max3_f32 v199, v186, v84, v85
	v_max3_f32 v200, v187, v102, v103
	s_nop 0
	s_waitcnt lgkmcnt(8)
	v_mfma_f32_32x32x16_bf16 v[50:65], v[12:15], v[194:197], v[50:65]
	ds_read_b64_tr_b16 v[186:187], v246 offset:52224
	ds_read_b64_tr_b16 v[188:189], v246 offset:52736
	v_max3_f32 v199, v199, v104, v105
	v_max3_f32 v200, v200, v86, v87
	s_nop 0
	s_waitcnt lgkmcnt(7)
	v_mfma_f32_32x32x16_bf16 v[66:81], v[12:15], v[178:181], v[66:81]
	ds_read_b64_tr_b16 v[190:191], v246 offset:56320
	ds_read_b64_tr_b16 v[192:193], v246 offset:56832
	v_max3_f32 v194, v199, v88, v89
	v_max3_f32 v195, v200, v106, v107
	s_nop 0
	s_waitcnt lgkmcnt(6)
	v_mfma_f32_32x32x16_bf16 v[18:33], v[4:7], v[182:185], v[18:33]
	v_max3_f32 v12, v194, v108, v109
	v_max3_f32 v13, v195, v90, v91
	s_nop 0
	s_waitcnt lgkmcnt(4)
	v_mfma_f32_32x32x16_bf16 v[34:49], v[4:7], v[8:11], v[34:49]
	v_max3_f32 v12, v12, v92, v93
	v_max3_f32 v13, v13, v110, v111
	s_nop 0
	s_waitcnt lgkmcnt(2)
	v_mfma_f32_32x32x16_bf16 v[50:65], v[4:7], v[186:189], v[50:65]
	v_max3_f32 v8, v12, v112, v113
	v_max3_f32 v9, v13, v94, v95
	s_nop 0
	s_waitcnt lgkmcnt(0)
	v_mfma_f32_32x32x16_bf16 v[66:81], v[4:7], v[190:193], v[66:81]
	v_max3_f32 v8, v8, v96, v97
	s_nop 0
	v_max_f32_e32 v8, v8, v9
	s_nop 0
	s_add_u32 s58, s58, 0x180000
	s_addc_u32 s59, s59, 0
	s_add_u32 s50, s50, 0x180000
	s_waitcnt vmcnt(0) lgkmcnt(0)
	s_barrier
	s_addc_u32 s51, s51, 0
	v_mov_b32_e32 v4, v8
	v_add_f32_e32 v251, v17, v198
	s_cmp_lt_u32 s90, s89
	v_permlane32_swap_b32_e32 v8, v4
	v_max_f32_e32 v178, v8, v4
	s_cbranch_scc0 .LBB0_285

; #define SB() __builtin_amdgcn_sched_barrier(0)
; #define MF32(a,b,c) __builtin_amdgcn_mfma_f32_32x32x16_bf16(a,b,c,0,0,0)
; #define EXP1(x) x=__builtin_amdgcn_exp2f((x)-mh_)
; __device__ __forceinline__ bf16x8 vfrag(lds_cptr vp,int i){ const s16x4 lo=vtr(vp+(i&3)*4096+(i>>2)*1024), hh=vtr(vp+(i&3)*4096+(i>>2)*1024+512); return (bf16x8){lo[0],lo[1],lo[2],lo[3],hh[0],hh[1],hh[2],hh[3]}; }
; __device__ __forceinline__ u32x4 packw(const f32x16&p,int base){ u32x4 w; w[0]=cvtpk_s(p[base],p[base+1]); w[1]=cvtpk_s(p[base+2],p[base+3]); w[2]=cvtpk_s(p[base+4],p[base+5]); w[3]=cvtpk_s(p[base+6],p[base+7]); return w; }
;   #define KF(i) LDSQ(kpn+((i)>>1)*2048+((i)&1)*512)
;   #define QF(d0) LDSQ(qp+(d0)*1024)
; template<int THRL,bool FIRST> __device__ __forceinline__ void step_main(f32x16&p0,f32x16&p1,f32x16&n0,f32x16&n1,St&S,lds_cptr kpn,lds_cptr qp,lds_cptr vp,float*wsf,int r32,int hi,float&rm){
;     ...
;   bf16x8 ka=KF(0),kb=KF(1),kc=KF(2),kd=KF(3),qa=QF(0),qb=QF(1);
;   decide<THRL,FIRST>(rm,S,wsf,r32,hi);
;   u32x4 pw0,pw1,pw2,pw3; const float mh_=S.mhat; const f32x16 z=f32x16{};
;   SB();
;   n0=MF32(ka,qa,z); ka=KF(4); EXP1(p0[0]);EXP1(p0[1]);EXP1(p0[2]); SB();
;   n1=MF32(kb,qa,z); kb=KF(5); qa=QF(2); EXP1(p0[3]);EXP1(p0[4]);EXP1(p0[5]); SB();
;   n0=MF32(kc,qb,n0);   kc=KF(6); EXP1(p0[6]);EXP1(p0[7]);EXP1(p0[8]); SB();
;   n1=MF32(kd,qb,n1);   kd=KF(7); qb=QF(3); EXP1(p0[9]);EXP1(p0[10]);EXP1(p0[11]); SB();
;   bf16x8 vfa=vfrag(vp,0);
;   n0=MF32(ka,qa,n0);   EXP1(p0[12]);EXP1(p0[13]);EXP1(p0[14]); pw0=packw(p0,0); SB();
;   bf16x8 vfb=vfrag(vp,1);
;   n1=MF32(kb,qa,n1);   EXP1(p0[15]);EXP1(p1[0]);EXP1(p1[1]); SB();
;   bf16x8 vfc=vfrag(vp,2);
;   n0=MF32(kc,qb,n0);   EXP1(p1[2]);EXP1(p1[3]);EXP1(p1[4]); pw1=packw(p0,8); SB();
;   bf16x8 vfd=vfrag(vp,3);
;   n1=MF32(kd,qb,n1);   EXP1(p1[5]);EXP1(p1[6]);EXP1(p1[7]); SB();
.LBB0_282:
	s_add_i32 s4, s88, 0x2000
	s_cmpk_lg_i32 s88, 0x4000
	s_cselect_b32 s91, s4, 0
	v_mfma_f32_32x32x16_bf16 v[130:145], v[204:207], v[164:167], v[146:161]
	s_add_i32 s4, s91, s84
	s_mov_b32 s5, m0
	s_mov_b32 m0, s4
	s_nop 0
	global_load_lds_dwordx4 v252, s[58:59]
	s_mov_b32 m0, s5
	v_exp_f32_e32 v190, v98
	v_exp_f32_e32 v191, v99
	v_exp_f32_e32 v192, v100
	v_mfma_f32_32x32x16_bf16 v[114:129], v[208:211], v[164:167], v[146:161]
	v_exp_f32_e32 v193, v101
	v_exp_f32_e32 v194, v102
	v_exp_f32_e32 v195, v103
	v_mfma_f32_32x32x16_bf16 v[130:145], v[212:215], v[168:171], v[130:145]
	v_exp_f32_e32 v196, v104
	v_exp_f32_e32 v197, v105
	v_exp_f32_e32 v198, v106
	v_mfma_f32_32x32x16_bf16 v[114:129], v[216:219], v[168:171], v[114:129]
	s_mov_b32 s4, m0
	s_mov_b32 m0, s79
	s_nop 0
	global_load_lds_dwordx4 v250, s[50:51]
	s_mov_b32 m0, s4
	v_exp_f32_e32 v17, v107
	v_exp_f32_e32 v199, v108
	v_exp_f32_e32 v200, v109
	v_mfma_f32_32x32x16_bf16 v[130:145], v[220:223], v[172:175], v[130:145]
	v_exp_f32_e32 v201, v110
	ds_read_b64_tr_b16 v[4:5], v246 offset:24576
	ds_read_b64_tr_b16 v[6:7], v246 offset:25088
	v_exp_f32_e32 v202, v111
	v_exp_f32_e32 v178, v112
	v_cvt_pk_bf16_f32 v8, v190, v191
	v_cvt_pk_bf16_f32 v9, v192, v193
	v_cvt_pk_bf16_f32 v10, v194, v195
	v_cvt_pk_bf16_f32 v11, v196, v197
	v_mfma_f32_32x32x16_bf16 v[114:129], v[224:227], v[172:175], v[114:129]
	ds_read_b64_tr_b16 v[106:107], v246 offset:28672
	ds_read_b64_tr_b16 v[108:109], v246 offset:29184
	v_exp_f32_e32 v180, v82
	v_exp_f32_e32 v179, v113
	v_exp_f32_e32 v181, v83
	v_mfma_f32_32x32x16_bf16 v[130:145], v[228:231], v[236:239], v[130:145]
	ds_read_b64_tr_b16 v[110:111], v246 offset:32768
	ds_read_b64_tr_b16 v[112:113], v246 offset:33280
	s_add_u32 s60, s50, 0x80
	s_addc_u32 s61, s51, 0
	s_mov_b32 s4, m0
	s_mov_b32 m0, s41
	s_nop 0
	global_load_lds_dwordx4 v250, s[60:61]
	s_mov_b32 m0, s4
	v_exp_f32_e32 v182, v84
	v_exp_f32_e32 v183, v85
	v_exp_f32_e32 v184, v86
	v_cvt_pk_bf16_f32 v82, v198, v17
	v_cvt_pk_bf16_f32 v83, v199, v200
	v_cvt_pk_bf16_f32 v84, v201, v202
	v_cvt_pk_bf16_f32 v85, v178, v179
	v_mfma_f32_32x32x16_bf16 v[114:129], v[232:235], v[236:239], v[114:129]
	v_add_u32_e32 v240, s88, v249
	ds_read_b64_tr_b16 v[98:99], v246 offset:36864
	ds_read_b64_tr_b16 v[100:101], v246 offset:37376
	v_exp_f32_e32 v185, v87
	v_exp_f32_e32 v186, v88
	v_exp_f32_e32 v187, v89
	s_waitcnt lgkmcnt(6)
	v_mfma_f32_32x32x16_bf16 v[18:33], v[8:11], v[4:7], v[18:33]
	ds_read_b128 v[204:207], v240
	v_add_f32_e32 v86, v190, v191
	ds_read_b64_tr_b16 v[12:13], v246 offset:25600
	ds_read_b64_tr_b16 v[14:15], v246 offset:26112
	v_add_f32_e32 v86, v192, v86
	v_exp_f32_e32 v103, v91
	v_add_f32_e32 v4, v193, v86
	v_add_f32_e32 v4, v194, v4
	v_add_f32_e32 v86, v195, v4
	v_exp_f32_e32 v102, v90
	s_waitcnt lgkmcnt(7)
	v_mfma_f32_32x32x16_bf16 v[34:49], v[8:11], v[106:109], v[34:49]
	ds_read_b64_tr_b16 v[4:5], v246 offset:29696
	ds_read_b64_tr_b16 v[6:7], v246 offset:30208
	ds_read_b128 v[208:211], v240 offset:512
	v_add_f32_e32 v86, v196, v86
	v_add_f32_e32 v86, v197, v86
	v_add_f32_e32 v86, v198, v86
	v_exp_f32_e32 v104, v92
	v_add_f32_e32 v17, v17, v86
	v_exp_f32_e32 v105, v93
	s_waitcnt lgkmcnt(8)
	v_mfma_f32_32x32x16_bf16 v[50:65], v[8:11], v[110:113], v[50:65]
	ds_read_b64_tr_b16 v[86:87], v246 offset:33792
	ds_read_b64_tr_b16 v[88:89], v246 offset:34304
	ds_read_b128 v[212:215], v240 offset:2048
	v_add_f32_e32 v17, v199, v17
	v_add_f32_e32 v17, v200, v17
	v_add_f32_e32 v17, v201, v17
	v_exp_f32_e32 v106, v94
	v_add_f32_e32 v17, v202, v17
	v_exp_f32_e32 v107, v95
	s_waitcnt lgkmcnt(9)
	v_mfma_f32_32x32x16_bf16 v[66:81], v[8:11], v[98:101], v[66:81]
	ds_read_b64_tr_b16 v[90:91], v246 offset:37888
	ds_read_b64_tr_b16 v[92:93], v246 offset:38400
	ds_read_b128 v[216:219], v240 offset:2560
	v_add_f32_e32 v17, v178, v17
	v_add_f32_e32 v8, v179, v17
	v_add_f32_e32 v8, v180, v8
	v_exp_f32_e32 v108, v96
	v_add_f32_e32 v17, v181, v8
	v_exp_f32_e32 v109, v97
	s_waitcnt lgkmcnt(9)
; __device__ __forceinline__ float max3f(float a,float b,float c){float r;asm("v_max3_f32 %0, %1, %2, %3":"=v"(r):"v"(a),"v"(b),"v"(c));return r;}
; __device__ __forceinline__ float max2f(float a,float b){float r;asm("v_max_f32_e32 %0, %1, %2":"=v"(r):"v"(a),"v"(b));return r;}
;   #define PVG(i,PW,VF,NEXTI,X0,X1,Y0,Y1,EXTRA) do{ S.o[(i)&3]=MF32(__builtin_bit_cast(bf16x8,PW),VF,S.o[(i)&3]); if((NEXTI)<16){ VF=vfrag(vp,(NEXTI)<16?(NEXTI):0); } sa+=X0; sa+=X1; sa+=Y0; sa+=Y1; EXTRA; SB(); }while(0)
;   #define PINAB() asm volatile("":"+v"(ma),"+v"(mb))
; template<int THRL,bool FIRST> __device__ __forceinline__ void step_main(f32x16&p0,f32x16&p1,f32x16&n0,f32x16&n1,St&S,lds_cptr kpn,lds_cptr qp,lds_cptr vp,float*wsf,int r32,int hi,float&rm){
;     ...
;   PVG(7,pw1,vfd,11, p1[14],p1[15],0.f,0.f, do{}while(0));
;   float ma,mb;
;     ...
;   PVG(8,pw2,vfa,12,0.f,0.f,0.f,0.f, do{ma=max3f(n0[0],n0[1],n1[0]);mb=max3f(n0[2],n0[3],n1[1]);PINAB();}while(0));
;   PVG(9,pw2,vfb,13,0.f,0.f,0.f,0.f, do{ma=max3f(ma,n1[2],n1[3]);mb=max3f(mb,n0[4],n0[5]);PINAB();}while(0));
;   PVG(10,pw2,vfc,14,0.f,0.f,0.f,0.f, do{ma=max3f(ma,n0[6],n0[7]);mb=max3f(mb,n1[4],n1[5]);PINAB();}while(0));
;   PVG(11,pw2,vfd,15,0.f,0.f,0.f,0.f, do{ma=max3f(ma,n1[6],n1[7]);mb=max3f(mb,n0[8],n0[9]);PINAB();}while(0));
;   PVG(12,pw3,vfa,16,0.f,0.f,0.f,0.f, do{ma=max3f(ma,n0[10],n0[11]);mb=max3f(mb,n1[8],n1[9]);PINAB();}while(0));
;   PVG(13,pw3,vfb,16,0.f,0.f,0.f,0.f, do{ma=max3f(ma,n1[10],n1[11]);mb=max3f(mb,n0[12],n0[13]);PINAB();}while(0));
;   PVG(14,pw3,vfc,16,0.f,0.f,0.f,0.f, do{ma=max3f(ma,n0[14],n0[15]);mb=max3f(mb,n1[12],n1[13]);PINAB();}while(0));
;   PVG(15,pw3,vfd,16,0.f,0.f,0.f,0.f, do{ma=max3f(ma,n1[14],n1[15]);ma=max2f(ma,mb);PINAB();}while(0));
;     ...
;   { auto rr=__builtin_amdgcn_permlane32_swap(__float_as_uint(ma),__float_as_uint(ma),false,false); rm=max2f(__uint_as_float(rr[0]),__uint_as_float(rr[1])); }
	v_mfma_f32_32x32x16_bf16 v[18:33], v[82:85], v[12:15], v[18:33]
	ds_read_b64_tr_b16 v[8:9], v246 offset:26624
	ds_read_b64_tr_b16 v[10:11], v246 offset:27136
	ds_read_b128 v[220:223], v240 offset:4096
	v_add_f32_e32 v17, v182, v17
	v_add_f32_e32 v17, v183, v17
	v_add_f32_e32 v17, v184, v17
	v_add_f32_e32 v17, v185, v17
	v_cvt_pk_bf16_f32 v12, v180, v181
	v_cvt_pk_bf16_f32 v13, v182, v183
	v_cvt_pk_bf16_f32 v14, v184, v185
	v_cvt_pk_bf16_f32 v15, v186, v187
	s_waitcnt lgkmcnt(10)
	v_mfma_f32_32x32x16_bf16 v[34:49], v[82:85], v[4:7], v[34:49]
	ds_read_b64_tr_b16 v[94:95], v246 offset:30720
	ds_read_b64_tr_b16 v[96:97], v246 offset:31232
	ds_read_b128 v[224:227], v240 offset:4608
	v_add_f32_e32 v17, v186, v17
	v_add_f32_e32 v17, v187, v17
	v_add_f32_e32 v17, v102, v17
	v_add_f32_e32 v17, v103, v17
	v_cvt_pk_bf16_f32 v4, v102, v103
	v_cvt_pk_bf16_f32 v5, v104, v105
	v_cvt_pk_bf16_f32 v6, v106, v107
	v_cvt_pk_bf16_f32 v7, v108, v109
	s_waitcnt lgkmcnt(10)
	v_mfma_f32_32x32x16_bf16 v[50:65], v[82:85], v[86:89], v[50:65]
	ds_read_b64_tr_b16 v[98:99], v246 offset:34816
	ds_read_b64_tr_b16 v[100:101], v246 offset:35328
	ds_read_b128 v[228:231], v240 offset:6144
	v_add_f32_e32 v17, v104, v17
	v_add_f32_e32 v17, v105, v17
	v_add_f32_e32 v17, v106, v17
	v_add_f32_e32 v17, v107, v17
	s_waitcnt lgkmcnt(10)
	v_mfma_f32_32x32x16_bf16 v[66:81], v[82:85], v[90:93], v[66:81]
	ds_read_b64_tr_b16 v[86:87], v246 offset:38912
	ds_read_b64_tr_b16 v[88:89], v246 offset:39424
	ds_read_b128 v[232:235], v240 offset:6656
	v_add_f32_e32 v17, v108, v17
	v_add_f32_e32 v17, v109, v17
	v_add_f32_e32 v17, 0, v17
	s_waitcnt lgkmcnt(10)
	v_mfma_f32_32x32x16_bf16 v[18:33], v[12:15], v[8:11], v[18:33]
	ds_read_b64_tr_b16 v[82:83], v246 offset:27648
	ds_read_b64_tr_b16 v[84:85], v246 offset:28160
	v_max3_f32 v90, v130, v131, v114
	v_max3_f32 v91, v132, v133, v115
	s_nop 0
	s_waitcnt lgkmcnt(9)
	v_mfma_f32_32x32x16_bf16 v[34:49], v[12:15], v[94:97], v[34:49]
	ds_read_b64_tr_b16 v[8:9], v246 offset:31744
	ds_read_b64_tr_b16 v[10:11], v246 offset:32256
	v_max3_f32 v102, v90, v116, v117
	v_max3_f32 v103, v91, v134, v135
	s_nop 0
	s_waitcnt lgkmcnt(8)
	v_mfma_f32_32x32x16_bf16 v[50:65], v[12:15], v[98:101], v[50:65]
	ds_read_b64_tr_b16 v[90:91], v246 offset:35840
	ds_read_b64_tr_b16 v[92:93], v246 offset:36352
	v_max3_f32 v102, v102, v136, v137
	v_max3_f32 v103, v103, v118, v119
	s_nop 0
	s_waitcnt lgkmcnt(7)
	v_mfma_f32_32x32x16_bf16 v[66:81], v[12:15], v[86:89], v[66:81]
	ds_read_b64_tr_b16 v[94:95], v246 offset:39936
	ds_read_b64_tr_b16 v[96:97], v246 offset:40448
	v_max3_f32 v98, v102, v120, v121
	v_max3_f32 v99, v103, v138, v139
	s_nop 0
	s_waitcnt lgkmcnt(6)
	v_mfma_f32_32x32x16_bf16 v[18:33], v[4:7], v[82:85], v[18:33]
	v_max3_f32 v12, v98, v140, v141
	v_max3_f32 v13, v99, v122, v123
	s_nop 0
	s_waitcnt lgkmcnt(4)
	v_mfma_f32_32x32x16_bf16 v[34:49], v[4:7], v[8:11], v[34:49]
	v_max3_f32 v12, v12, v124, v125
	v_max3_f32 v13, v13, v142, v143
	s_nop 0
	s_waitcnt lgkmcnt(2)
	v_mfma_f32_32x32x16_bf16 v[50:65], v[4:7], v[90:93], v[50:65]
	v_max3_f32 v8, v12, v144, v145
	v_max3_f32 v9, v13, v126, v127
	s_nop 0
	s_waitcnt lgkmcnt(0)
	v_mfma_f32_32x32x16_bf16 v[66:81], v[4:7], v[94:97], v[66:81]
	v_max3_f32 v8, v8, v128, v129
	s_nop 0
	v_max_f32_e32 v8, v8, v9
	s_nop 0
	v_mov_b32_e32 v162, v8
	v_mov_b32_e32 v163, v8
	s_waitcnt vmcnt(0) lgkmcnt(0)
	s_barrier
	v_permlane32_swap_b32_e32 v162, v163
	v_max_f32_e32 v94, v162, v163
	v_add_f32_e32 v17, v251, v17
	v_cmp_lt_f32_e32 vcc, s69, v94
	s_cbranch_vccz .LBB0_277
	v_max_f32_e32 v94, v94, v94
	v_max_f32_e32 v94, 0, v94
	v_exp_f32_e64 v95, -v94
	s_and_saveexec_b64 s[60:61], s[6:7]
	s_cbranch_execz .LBB0_276
	ds_write_b32 v16, v95
	s_branch .LBB0_276

; #define SB() __builtin_amdgcn_sched_barrier(0)
; #define MF32(a,b,c) __builtin_amdgcn_mfma_f32_32x32x16_bf16(a,b,c,0,0,0)
; #define EXP1(x) x=__builtin_amdgcn_exp2f((x)-mh_)
; __device__ __forceinline__ bf16x8 vfrag(lds_cptr vp,int i){ const s16x4 lo=vtr(vp+(i&3)*4096+(i>>2)*1024), hh=vtr(vp+(i&3)*4096+(i>>2)*1024+512); return (bf16x8){lo[0],lo[1],lo[2],lo[3],hh[0],hh[1],hh[2],hh[3]}; }
; __device__ __forceinline__ u32x4 packw(const f32x16&p,int base){ u32x4 w; w[0]=cvtpk_s(p[base],p[base+1]); w[1]=cvtpk_s(p[base+2],p[base+3]); w[2]=cvtpk_s(p[base+4],p[base+5]); w[3]=cvtpk_s(p[base+6],p[base+7]); return w; }
;   #define KF(i) LDSQ(kpn+((i)>>1)*2048+((i)&1)*512)
;   #define QF(d0) LDSQ(qp+(d0)*1024)
; template<int THRL,bool FIRST> __device__ __forceinline__ void step_main(f32x16&p0,f32x16&p1,f32x16&n0,f32x16&n1,St&S,lds_cptr kpn,lds_cptr qp,lds_cptr vp,float*wsf,int r32,int hi,float&rm){
;     ...
;   bf16x8 ka=KF(0),kb=KF(1),kc=KF(2),kd=KF(3),qa=QF(0),qb=QF(1);
;   decide<THRL,FIRST>(rm,S,wsf,r32,hi);
;   u32x4 pw0,pw1,pw2,pw3; const float mh_=S.mhat; const f32x16 z=f32x16{};
;   SB();
;   n0=MF32(ka,qa,z); ka=KF(4); EXP1(p0[0]);EXP1(p0[1]);EXP1(p0[2]); SB();
;   n1=MF32(kb,qa,z); kb=KF(5); qa=QF(2); EXP1(p0[3]);EXP1(p0[4]);EXP1(p0[5]); SB();
;   n0=MF32(kc,qb,n0);   kc=KF(6); EXP1(p0[6]);EXP1(p0[7]);EXP1(p0[8]); SB();
;   n1=MF32(kd,qb,n1);   kd=KF(7); qb=QF(3); EXP1(p0[9]);EXP1(p0[10]);EXP1(p0[11]); SB();
;   bf16x8 vfa=vfrag(vp,0);
;   n0=MF32(ka,qa,n0);   EXP1(p0[12]);EXP1(p0[13]);EXP1(p0[14]); pw0=packw(p0,0); SB();
;   bf16x8 vfb=vfrag(vp,1);
;   n1=MF32(kb,qa,n1);   EXP1(p0[15]);EXP1(p1[0]);EXP1(p1[1]); SB();
;   bf16x8 vfc=vfrag(vp,2);
;   n0=MF32(kc,qb,n0);   EXP1(p1[2]);EXP1(p1[3]);EXP1(p1[4]); pw1=packw(p0,8); SB();
;   bf16x8 vfd=vfrag(vp,3);
;   n1=MF32(kd,qb,n1);   EXP1(p1[5]);EXP1(p1[6]);EXP1(p1[7]); SB();
.LBB0_435:
	s_add_i32 s4, s89, 0x2000
	s_cmpk_lg_i32 s89, 0x4000
	s_cselect_b32 s86, s4, 0
	s_add_i32 s88, s88, 2
	v_mfma_f32_32x32x16_bf16 v[98:113], v[204:207], v[164:167], v[146:161]
	s_add_i32 s4, s86, s80
	s_add_u32 s58, s50, 0xc0000
	s_addc_u32 s59, s51, 0
	s_mov_b32 s5, m0
	s_mov_b32 m0, s4
	s_nop 0
	global_load_lds_dwordx4 v252, s[58:59]
	s_mov_b32 m0, s5
	v_exp_f32_e32 v130, v130
	v_exp_f32_e32 v131, v131
	v_exp_f32_e32 v132, v132
	v_exp_f32_e32 v133, v133
	v_exp_f32_e32 v134, v134
	v_exp_f32_e32 v135, v135
	v_mfma_f32_32x32x16_bf16 v[82:97], v[208:211], v[164:167], v[146:161]
	v_mfma_f32_32x32x16_bf16 v[98:113], v[212:215], v[168:171], v[98:113]
	v_exp_f32_e32 v136, v136
	v_exp_f32_e32 v137, v137
	v_exp_f32_e32 v138, v138
	v_mfma_f32_32x32x16_bf16 v[82:97], v[216:219], v[168:171], v[82:97]
	s_add_u32 s58, s48, 0xc0000
	s_addc_u32 s59, s49, 0
	s_mov_b32 s4, m0
	s_mov_b32 m0, s78
	s_nop 0
	global_load_lds_dwordx4 v250, s[58:59]
	s_mov_b32 m0, s4
	v_exp_f32_e32 v139, v139
	v_exp_f32_e32 v140, v140
	v_exp_f32_e32 v141, v141
	v_mfma_f32_32x32x16_bf16 v[98:113], v[220:223], v[172:175], v[98:113]
	v_exp_f32_e32 v142, v142
	ds_read_b64_tr_b16 v[4:5], v246 offset:40960
	ds_read_b64_tr_b16 v[6:7], v246 offset:41472
	v_exp_f32_e32 v143, v143
	v_exp_f32_e32 v144, v144
	v_cvt_pk_bf16_f32 v8, v130, v131
	v_cvt_pk_bf16_f32 v9, v132, v133
	v_cvt_pk_bf16_f32 v10, v134, v135
	v_cvt_pk_bf16_f32 v11, v136, v137
	v_mfma_f32_32x32x16_bf16 v[82:97], v[224:227], v[172:175], v[82:97]
	ds_read_b64_tr_b16 v[178:179], v246 offset:45056
	ds_read_b64_tr_b16 v[180:181], v246 offset:45568
	v_exp_f32_e32 v145, v145
	v_exp_f32_e32 v114, v114
	v_exp_f32_e32 v115, v115
	v_mfma_f32_32x32x16_bf16 v[98:113], v[228:231], v[236:239], v[98:113]
	ds_read_b64_tr_b16 v[182:183], v246 offset:49152
	ds_read_b64_tr_b16 v[184:185], v246 offset:49664
	s_add_u32 s58, s48, 0xc0080
	s_addc_u32 s59, s49, 0
	s_mov_b32 s4, m0
	s_mov_b32 m0, s79
	s_nop 0
	global_load_lds_dwordx4 v250, s[58:59]
	s_mov_b32 m0, s4
	v_exp_f32_e32 v116, v116
	v_exp_f32_e32 v117, v117
	v_exp_f32_e32 v118, v118
	v_cvt_pk_bf16_f32 v186, v138, v139
	v_cvt_pk_bf16_f32 v187, v140, v141
	v_cvt_pk_bf16_f32 v188, v142, v143
	v_cvt_pk_bf16_f32 v189, v144, v145
	v_mfma_f32_32x32x16_bf16 v[82:97], v[232:235], v[236:239], v[82:97]
	v_add_u32_e32 v240, s89, v249
	ds_read_b64_tr_b16 v[190:191], v246 offset:53248
	ds_read_b64_tr_b16 v[192:193], v246 offset:53760
	v_exp_f32_e32 v119, v119
	v_exp_f32_e32 v120, v120
	v_exp_f32_e32 v121, v121
	s_waitcnt lgkmcnt(6)
	v_mfma_f32_32x32x16_bf16 v[18:33], v[8:11], v[4:7], v[18:33]
	ds_read_b64_tr_b16 v[12:13], v246 offset:41984
	ds_read_b64_tr_b16 v[14:15], v246 offset:42496
	ds_read_b128 v[204:207], v240
	v_add_f32_e32 v194, v130, v131
	v_exp_f32_e32 v122, v122
	v_exp_f32_e32 v123, v123
	v_add_f32_e32 v194, v132, v194
	v_add_f32_e32 v4, v133, v194
	v_add_f32_e32 v4, v134, v4
	v_add_f32_e32 v194, v135, v4
	s_waitcnt lgkmcnt(7)
	v_mfma_f32_32x32x16_bf16 v[34:49], v[8:11], v[178:181], v[34:49]
	ds_read_b64_tr_b16 v[4:5], v246 offset:46080
	ds_read_b64_tr_b16 v[6:7], v246 offset:46592
	ds_read_b128 v[208:211], v240 offset:512
	v_exp_f32_e32 v124, v124
	v_exp_f32_e32 v125, v125
	v_add_f32_e32 v194, v136, v194
	v_add_f32_e32 v178, v137, v194
	v_add_f32_e32 v178, v138, v178
	v_add_f32_e32 v194, v139, v178
	s_waitcnt lgkmcnt(8)
	v_mfma_f32_32x32x16_bf16 v[50:65], v[8:11], v[182:185], v[50:65]
	ds_read_b64_tr_b16 v[178:179], v246 offset:50176
	ds_read_b64_tr_b16 v[180:181], v246 offset:50688
	ds_read_b128 v[212:215], v240 offset:2048
	v_exp_f32_e32 v126, v126
	v_exp_f32_e32 v127, v127
	v_add_f32_e32 v194, v140, v194
	v_add_f32_e32 v182, v141, v194
	v_add_f32_e32 v182, v142, v182
	v_add_f32_e32 v194, v143, v182
	s_waitcnt lgkmcnt(9)
; #define EXP1(x) x=__builtin_amdgcn_exp2f((x)-mh_)
; template<int THRL,bool FIRST> __device__ __forceinline__ void step_main(f32x16&p0,f32x16&p1,f32x16&n0,f32x16&n1,St&S,lds_cptr kpn,lds_cptr qp,lds_cptr vp,float*wsf,int r32,int hi,float&rm){
;     ...
;   PVG(0,pw0,vfa,4, p0[2],p0[3],p0[4],p0[5],   do{EXP1(p1[8]);EXP1(p1[9]);}while(0));
;   PVG(1,pw0,vfb,5, p0[6],p0[7],p0[8],p0[9], do{EXP1(p1[10]);EXP1(p1[11]);}while(0));
;   PVG(2,pw0,vfc,6, p0[10],p0[11],p0[12],p0[13], do{EXP1(p1[12]);EXP1(p1[13]);}while(0));
;   PVG(3,pw0,vfd,7, p0[14],p0[15],p1[0],p1[1],   do{EXP1(p1[14]);EXP1(p1[15]);}while(0));
;   PVG(4,pw1,vfa,8, p1[2],p1[3],p1[4],p1[5],   pw2=packw(p1,0));
;   PVG(5,pw1,vfb,9, p1[6],p1[7],p1[8],p1[9], pw3=packw(p1,8));
;   PVG(6,pw1,vfc,10, p1[10],p1[11],p1[12],p1[13], do{}while(0));
;   PVG(7,pw1,vfd,11, p1[14],p1[15],0.f,0.f, do{}while(0));
;   float ma,mb;
;     ...
;   PVG(8,pw2,vfa,12,0.f,0.f,0.f,0.f, do{ma=max3f(n0[0],n0[1],n1[0]);mb=max3f(n0[2],n0[3],n1[1]);PINAB();}while(0));
;   PVG(9,pw2,vfb,13,0.f,0.f,0.f,0.f, do{ma=max3f(ma,n1[2],n1[3]);mb=max3f(mb,n0[4],n0[5]);PINAB();}while(0));
;   PVG(10,pw2,vfc,14,0.f,0.f,0.f,0.f, do{ma=max3f(ma,n0[6],n0[7]);mb=max3f(mb,n1[4],n1[5]);PINAB();}while(0));
;   PVG(11,pw2,vfd,15,0.f,0.f,0.f,0.f, do{ma=max3f(ma,n1[6],n1[7]);mb=max3f(mb,n0[8],n0[9]);PINAB();}while(0));
;   PVG(12,pw3,vfa,16,0.f,0.f,0.f,0.f, do{ma=max3f(ma,n0[10],n0[11]);mb=max3f(mb,n1[8],n1[9]);PINAB();}while(0));
;   PVG(13,pw3,vfb,16,0.f,0.f,0.f,0.f, do{ma=max3f(ma,n1[10],n1[11]);mb=max3f(mb,n0[12],n0[13]);PINAB();}while(0));
;   PVG(14,pw3,vfc,16,0.f,0.f,0.f,0.f, do{ma=max3f(ma,n0[14],n0[15]);mb=max3f(mb,n1[12],n1[13]);PINAB();}while(0));
;   PVG(15,pw3,vfd,16,0.f,0.f,0.f,0.f, do{ma=max3f(ma,n1[14],n1[15]);ma=max2f(ma,mb);PINAB();}while(0));
;     ...
;   { auto rr=__builtin_amdgcn_permlane32_swap(__float_as_uint(ma),__float_as_uint(ma),false,false); rm=max2f(__uint_as_float(rr[0]),__uint_as_float(rr[1])); }
;     ...
;   S.l_reg+=sa;
; template<int THRL> __device__ __forceinline__ void unit(int qb,const bf16*Q,const bf16*K,const bf16*V,bf16*O,char*shm){
;     ...
;     for(t=2;t<NT-4;t+=2){
;       DMA_K(t+2,ks2); DMA_V(t+1,VBUF);
;       step_main<THRL,false>(pA0,pA1,pB0,pB1,S,kp0+ks1,qp,vp0,wsf,r32,hi,rm); A128_WAITBAR(); ROT();
;       DMA_K(t+3,ks2); DMA_V(t+2,0);
;       step_main<THRL,false>(pB0,pB1,pA0,pA1,S,kp0+ks1,qp,vp0+VBUF,wsf,r32,hi,rm); A128_WAITBAR(); ROT();
;     }
	v_mfma_f32_32x32x16_bf16 v[66:81], v[8:11], v[190:193], v[66:81]
	ds_read_b64_tr_b16 v[182:183], v246 offset:54272
	ds_read_b64_tr_b16 v[184:185], v246 offset:54784
	ds_read_b128 v[216:219], v240 offset:2560
	v_exp_f32_e32 v128, v128
	v_exp_f32_e32 v129, v129
	v_add_f32_e32 v194, v144, v194
	v_add_f32_e32 v8, v145, v194
	v_add_f32_e32 v8, v114, v8
	v_add_f32_e32 v190, v115, v8
	s_waitcnt lgkmcnt(10)
	v_mfma_f32_32x32x16_bf16 v[18:33], v[186:189], v[12:15], v[18:33]
	ds_read_b64_tr_b16 v[8:9], v246 offset:43008
	ds_read_b64_tr_b16 v[10:11], v246 offset:43520
	ds_read_b128 v[220:223], v240 offset:4096
	v_add_f32_e32 v190, v116, v190
	v_add_f32_e32 v190, v117, v190
	v_add_f32_e32 v190, v118, v190
	v_add_f32_e32 v194, v119, v190
	v_cvt_pk_bf16_f32 v12, v114, v115
	v_cvt_pk_bf16_f32 v13, v116, v117
	v_cvt_pk_bf16_f32 v14, v118, v119
	v_cvt_pk_bf16_f32 v15, v120, v121
	s_waitcnt lgkmcnt(10)
	v_mfma_f32_32x32x16_bf16 v[34:49], v[186:189], v[4:7], v[34:49]
	ds_read_b64_tr_b16 v[190:191], v246 offset:47104
	ds_read_b64_tr_b16 v[192:193], v246 offset:47616
	ds_read_b128 v[224:227], v240 offset:4608
	v_add_f32_e32 v194, v120, v194
	v_add_f32_e32 v194, v121, v194
	v_add_f32_e32 v194, v122, v194
	v_add_f32_e32 v198, v123, v194
	v_cvt_pk_bf16_f32 v4, v122, v123
	v_cvt_pk_bf16_f32 v5, v124, v125
	v_cvt_pk_bf16_f32 v6, v126, v127
	v_cvt_pk_bf16_f32 v7, v128, v129
	s_waitcnt lgkmcnt(10)
	v_mfma_f32_32x32x16_bf16 v[50:65], v[186:189], v[178:181], v[50:65]
	ds_read_b64_tr_b16 v[194:195], v246 offset:51200
	ds_read_b64_tr_b16 v[196:197], v246 offset:51712
	ds_read_b128 v[228:231], v240 offset:6144
	v_add_f32_e32 v198, v124, v198
	v_add_f32_e32 v198, v125, v198
	v_add_f32_e32 v198, v126, v198
	v_add_f32_e32 v198, v127, v198
	s_waitcnt lgkmcnt(10)
	v_mfma_f32_32x32x16_bf16 v[66:81], v[186:189], v[182:185], v[66:81]
	ds_read_b64_tr_b16 v[178:179], v246 offset:55296
	ds_read_b64_tr_b16 v[180:181], v246 offset:55808
	ds_read_b128 v[232:235], v240 offset:6656
	v_add_f32_e32 v198, v128, v198
	v_add_f32_e32 v198, v129, v198
	v_add_f32_e32 v198, 0, v198
	s_waitcnt lgkmcnt(10)
	v_mfma_f32_32x32x16_bf16 v[18:33], v[12:15], v[8:11], v[18:33]
	ds_read_b64_tr_b16 v[182:183], v246 offset:44032
	ds_read_b64_tr_b16 v[184:185], v246 offset:44544
	v_max3_f32 v186, v98, v99, v82
	v_max3_f32 v187, v100, v101, v83
	s_nop 0
	s_waitcnt lgkmcnt(9)
	v_mfma_f32_32x32x16_bf16 v[34:49], v[12:15], v[190:193], v[34:49]
	ds_read_b64_tr_b16 v[8:9], v246 offset:48128
	ds_read_b64_tr_b16 v[10:11], v246 offset:48640
	v_max3_f32 v199, v186, v84, v85
	v_max3_f32 v200, v187, v102, v103
	s_nop 0
	s_waitcnt lgkmcnt(8)
	v_mfma_f32_32x32x16_bf16 v[50:65], v[12:15], v[194:197], v[50:65]
	ds_read_b64_tr_b16 v[186:187], v246 offset:52224
	ds_read_b64_tr_b16 v[188:189], v246 offset:52736
	v_max3_f32 v199, v199, v104, v105
	v_max3_f32 v200, v200, v86, v87
	s_nop 0
	s_waitcnt lgkmcnt(7)
	v_mfma_f32_32x32x16_bf16 v[66:81], v[12:15], v[178:181], v[66:81]
	ds_read_b64_tr_b16 v[190:191], v246 offset:56320
	ds_read_b64_tr_b16 v[192:193], v246 offset:56832
	v_max3_f32 v194, v199, v88, v89
	v_max3_f32 v195, v200, v106, v107
	s_nop 0
	s_waitcnt lgkmcnt(6)
	v_mfma_f32_32x32x16_bf16 v[18:33], v[4:7], v[182:185], v[18:33]
	v_max3_f32 v12, v194, v108, v109
	v_max3_f32 v13, v195, v90, v91
	s_nop 0
	s_waitcnt lgkmcnt(4)
	v_mfma_f32_32x32x16_bf16 v[34:49], v[4:7], v[8:11], v[34:49]
	v_max3_f32 v12, v12, v92, v93
	v_max3_f32 v13, v13, v110, v111
	s_nop 0
	s_waitcnt lgkmcnt(2)
	v_mfma_f32_32x32x16_bf16 v[50:65], v[4:7], v[186:189], v[50:65]
	v_max3_f32 v8, v12, v112, v113
	v_max3_f32 v9, v13, v94, v95
	s_nop 0
	s_waitcnt lgkmcnt(0)
	v_mfma_f32_32x32x16_bf16 v[66:81], v[4:7], v[190:193], v[66:81]
	v_max3_f32 v8, v8, v96, v97
	s_nop 0
	v_max_f32_e32 v8, v8, v9
	s_nop 0
	s_add_u32 s50, s50, 0x180000
	s_addc_u32 s51, s51, 0
	s_add_u32 s48, s48, 0x180000
	s_waitcnt vmcnt(0) lgkmcnt(0)
	s_barrier
	s_addc_u32 s49, s49, 0
	v_mov_b32_e32 v4, v8
	v_add_f32_e32 v251, v17, v198
	s_cmp_lt_u32 s88, s87
	v_permlane32_swap_b32_e32 v8, v4
	v_max_f32_e32 v178, v8, v4
	s_cbranch_scc0 .LBB0_443

; #define SB() __builtin_amdgcn_sched_barrier(0)
; #define MF32(a,b,c) __builtin_amdgcn_mfma_f32_32x32x16_bf16(a,b,c,0,0,0)
; #define EXP1(x) x=__builtin_amdgcn_exp2f((x)-mh_)
; __device__ __forceinline__ bf16x8 vfrag(lds_cptr vp,int i){ const s16x4 lo=vtr(vp+(i&3)*4096+(i>>2)*1024), hh=vtr(vp+(i&3)*4096+(i>>2)*1024+512); return (bf16x8){lo[0],lo[1],lo[2],lo[3],hh[0],hh[1],hh[2],hh[3]}; }
; __device__ __forceinline__ u32x4 packw(const f32x16&p,int base){ u32x4 w; w[0]=cvtpk_s(p[base],p[base+1]); w[1]=cvtpk_s(p[base+2],p[base+3]); w[2]=cvtpk_s(p[base+4],p[base+5]); w[3]=cvtpk_s(p[base+6],p[base+7]); return w; }
;   #define KF(i) LDSQ(kpn+((i)>>1)*2048+((i)&1)*512)
;   #define QF(d0) LDSQ(qp+(d0)*1024)
; template<int THRL,bool FIRST> __device__ __forceinline__ void step_main(f32x16&p0,f32x16&p1,f32x16&n0,f32x16&n1,St&S,lds_cptr kpn,lds_cptr qp,lds_cptr vp,float*wsf,int r32,int hi,float&rm){
;     ...
;   bf16x8 ka=KF(0),kb=KF(1),kc=KF(2),kd=KF(3),qa=QF(0),qb=QF(1);
;   decide<THRL,FIRST>(rm,S,wsf,r32,hi);
;   u32x4 pw0,pw1,pw2,pw3; const float mh_=S.mhat; const f32x16 z=f32x16{};
;   SB();
;   n0=MF32(ka,qa,z); ka=KF(4); EXP1(p0[0]);EXP1(p0[1]);EXP1(p0[2]); SB();
;   n1=MF32(kb,qa,z); kb=KF(5); qa=QF(2); EXP1(p0[3]);EXP1(p0[4]);EXP1(p0[5]); SB();
;   n0=MF32(kc,qb,n0);   kc=KF(6); EXP1(p0[6]);EXP1(p0[7]);EXP1(p0[8]); SB();
;   n1=MF32(kd,qb,n1);   kd=KF(7); qb=QF(3); EXP1(p0[9]);EXP1(p0[10]);EXP1(p0[11]); SB();
;   bf16x8 vfa=vfrag(vp,0);
;   n0=MF32(ka,qa,n0);   EXP1(p0[12]);EXP1(p0[13]);EXP1(p0[14]); pw0=packw(p0,0); SB();
;   bf16x8 vfb=vfrag(vp,1);
;   n1=MF32(kb,qa,n1);   EXP1(p0[15]);EXP1(p1[0]);EXP1(p1[1]); SB();
;   bf16x8 vfc=vfrag(vp,2);
;   n0=MF32(kc,qb,n0);   EXP1(p1[2]);EXP1(p1[3]);EXP1(p1[4]); pw1=packw(p0,8); SB();
;   bf16x8 vfd=vfrag(vp,3);
;   n1=MF32(kd,qb,n1);   EXP1(p1[5]);EXP1(p1[6]);EXP1(p1[7]); SB();
;     ...
;   float sa=p0[0]+p0[1];
;     ...
;   PVG(0,pw0,vfa,4, p0[2],p0[3],p0[4],p0[5],   do{EXP1(p1[8]);EXP1(p1[9]);}while(0));
;   PVG(1,pw0,vfb,5, p0[6],p0[7],p0[8],p0[9], do{EXP1(p1[10]);EXP1(p1[11]);}while(0));
;   PVG(2,pw0,vfc,6, p0[10],p0[11],p0[12],p0[13], do{EXP1(p1[12]);EXP1(p1[13]);}while(0));
;   PVG(3,pw0,vfd,7, p0[14],p0[15],p1[0],p1[1],   do{EXP1(p1[14]);EXP1(p1[15]);}while(0));
.LBB0_440:
	s_add_i32 s4, s86, 0x2000
	s_cmpk_lg_i32 s86, 0x4000
	s_cselect_b32 s89, s4, 0
	v_mfma_f32_32x32x16_bf16 v[130:145], v[204:207], v[164:167], v[146:161]
	s_add_i32 s4, s89, s80
	s_mov_b32 s5, m0
	s_mov_b32 m0, s4
	s_nop 0
	global_load_lds_dwordx4 v252, s[50:51]
	s_mov_b32 m0, s5
	v_exp_f32_e32 v190, v98
	v_exp_f32_e32 v191, v99
	v_exp_f32_e32 v192, v100
	v_mfma_f32_32x32x16_bf16 v[114:129], v[208:211], v[164:167], v[146:161]
	v_exp_f32_e32 v193, v101
	v_exp_f32_e32 v194, v102
	v_exp_f32_e32 v195, v103
	v_mfma_f32_32x32x16_bf16 v[130:145], v[212:215], v[168:171], v[130:145]
	v_exp_f32_e32 v196, v104
	v_exp_f32_e32 v197, v105
	v_exp_f32_e32 v198, v106
	v_mfma_f32_32x32x16_bf16 v[114:129], v[216:219], v[168:171], v[114:129]
	s_mov_b32 s4, m0
	s_mov_b32 m0, s77
	s_nop 0
	global_load_lds_dwordx4 v250, s[48:49]
	s_mov_b32 m0, s4
	v_exp_f32_e32 v17, v107
	v_exp_f32_e32 v199, v108
	v_exp_f32_e32 v200, v109
	v_mfma_f32_32x32x16_bf16 v[130:145], v[220:223], v[172:175], v[130:145]
	v_exp_f32_e32 v201, v110
	ds_read_b64_tr_b16 v[4:5], v246 offset:24576
	ds_read_b64_tr_b16 v[6:7], v246 offset:25088
	v_exp_f32_e32 v202, v111
	v_exp_f32_e32 v178, v112
	v_cvt_pk_bf16_f32 v8, v190, v191
	v_cvt_pk_bf16_f32 v9, v192, v193
	v_cvt_pk_bf16_f32 v10, v194, v195
	v_cvt_pk_bf16_f32 v11, v196, v197
	v_mfma_f32_32x32x16_bf16 v[114:129], v[224:227], v[172:175], v[114:129]
	ds_read_b64_tr_b16 v[106:107], v246 offset:28672
	ds_read_b64_tr_b16 v[108:109], v246 offset:29184
	v_exp_f32_e32 v180, v82
	v_exp_f32_e32 v179, v113
	v_exp_f32_e32 v181, v83
	v_mfma_f32_32x32x16_bf16 v[130:145], v[228:231], v[236:239], v[130:145]
	ds_read_b64_tr_b16 v[110:111], v246 offset:32768
	ds_read_b64_tr_b16 v[112:113], v246 offset:33280
	s_add_u32 s58, s48, 0x80
	s_addc_u32 s59, s49, 0
	s_mov_b32 s4, m0
	s_mov_b32 m0, s39
	s_nop 0
	global_load_lds_dwordx4 v250, s[58:59]
	s_mov_b32 m0, s4
	v_exp_f32_e32 v182, v84
	v_exp_f32_e32 v183, v85
	v_exp_f32_e32 v184, v86
	v_cvt_pk_bf16_f32 v82, v198, v17
	v_cvt_pk_bf16_f32 v83, v199, v200
	v_cvt_pk_bf16_f32 v84, v201, v202
	v_cvt_pk_bf16_f32 v85, v178, v179
	v_mfma_f32_32x32x16_bf16 v[114:129], v[232:235], v[236:239], v[114:129]
	v_add_u32_e32 v240, s86, v249
	ds_read_b64_tr_b16 v[98:99], v246 offset:36864
	ds_read_b64_tr_b16 v[100:101], v246 offset:37376
	v_exp_f32_e32 v185, v87
	v_exp_f32_e32 v186, v88
	v_exp_f32_e32 v187, v89
	s_waitcnt lgkmcnt(6)
	v_mfma_f32_32x32x16_bf16 v[18:33], v[8:11], v[4:7], v[18:33]
	ds_read_b128 v[204:207], v240
	v_add_f32_e32 v86, v190, v191
	ds_read_b64_tr_b16 v[12:13], v246 offset:25600
	ds_read_b64_tr_b16 v[14:15], v246 offset:26112
	v_add_f32_e32 v86, v192, v86
	v_exp_f32_e32 v103, v91
	v_add_f32_e32 v4, v193, v86
	v_add_f32_e32 v4, v194, v4
	v_add_f32_e32 v86, v195, v4
	v_exp_f32_e32 v102, v90
	s_waitcnt lgkmcnt(7)
	v_mfma_f32_32x32x16_bf16 v[34:49], v[8:11], v[106:109], v[34:49]
	ds_read_b64_tr_b16 v[4:5], v246 offset:29696
	ds_read_b64_tr_b16 v[6:7], v246 offset:30208
	ds_read_b128 v[208:211], v240 offset:512
	v_add_f32_e32 v86, v196, v86
	v_add_f32_e32 v86, v197, v86
	v_add_f32_e32 v86, v198, v86
	v_exp_f32_e32 v104, v92
	v_add_f32_e32 v17, v17, v86
	v_exp_f32_e32 v105, v93
	s_waitcnt lgkmcnt(8)
	v_mfma_f32_32x32x16_bf16 v[50:65], v[8:11], v[110:113], v[50:65]
	ds_read_b64_tr_b16 v[86:87], v246 offset:33792
	ds_read_b64_tr_b16 v[88:89], v246 offset:34304
	ds_read_b128 v[212:215], v240 offset:2048
	v_add_f32_e32 v17, v199, v17
	v_add_f32_e32 v17, v200, v17
	v_add_f32_e32 v17, v201, v17
	v_exp_f32_e32 v106, v94
	v_add_f32_e32 v17, v202, v17
	v_exp_f32_e32 v107, v95
	s_waitcnt lgkmcnt(9)
	v_mfma_f32_32x32x16_bf16 v[66:81], v[8:11], v[98:101], v[66:81]
	ds_read_b64_tr_b16 v[90:91], v246 offset:37888
	ds_read_b64_tr_b16 v[92:93], v246 offset:38400
	ds_read_b128 v[216:219], v240 offset:2560
	v_add_f32_e32 v17, v178, v17
	v_add_f32_e32 v8, v179, v17
	v_add_f32_e32 v8, v180, v8
	v_exp_f32_e32 v108, v96
	v_add_f32_e32 v17, v181, v8
	v_exp_f32_e32 v109, v97
	s_waitcnt lgkmcnt(9)
; __device__ __forceinline__ float max2f(float a,float b){float r;asm("v_max_f32_e32 %0, %1, %2":"=v"(r):"v"(a),"v"(b));return r;}
; template<int THRL,bool FIRST> __device__ __forceinline__ void decide(float rm,St&S,float*wsf,int r32,int hi){
;     ...
;   else if(__any(rm-S.mhat>(float)THRL)){
;     const float dl=__builtin_fmaxf(rm-S.mhat,0.f); S.mhat+=dl;
;     const float f=__builtin_amdgcn_exp2f(-dl); S.l_reg*=f; if(hi==0)wsf[r32]=f;
;     asm volatile("s_waitcnt lgkmcnt(0)":::"memory");
; template<int THRL,bool FIRST> __device__ __forceinline__ void step_main(f32x16&p0,f32x16&p1,f32x16&n0,f32x16&n1,St&S,lds_cptr kpn,lds_cptr qp,lds_cptr vp,float*wsf,int r32,int hi,float&rm){
;     ...
;   PVG(0,pw0,vfa,4, p0[2],p0[3],p0[4],p0[5],   do{EXP1(p1[8]);EXP1(p1[9]);}while(0));
;   PVG(1,pw0,vfb,5, p0[6],p0[7],p0[8],p0[9], do{EXP1(p1[10]);EXP1(p1[11]);}while(0));
;   PVG(2,pw0,vfc,6, p0[10],p0[11],p0[12],p0[13], do{EXP1(p1[12]);EXP1(p1[13]);}while(0));
;   PVG(3,pw0,vfd,7, p0[14],p0[15],p1[0],p1[1],   do{EXP1(p1[14]);EXP1(p1[15]);}while(0));
;   PVG(4,pw1,vfa,8, p1[2],p1[3],p1[4],p1[5],   pw2=packw(p1,0));
;   PVG(5,pw1,vfb,9, p1[6],p1[7],p1[8],p1[9], pw3=packw(p1,8));
;   PVG(6,pw1,vfc,10, p1[10],p1[11],p1[12],p1[13], do{}while(0));
;   PVG(7,pw1,vfd,11, p1[14],p1[15],0.f,0.f, do{}while(0));
;   float ma,mb;
;     ...
;   PVG(8,pw2,vfa,12,0.f,0.f,0.f,0.f, do{ma=max3f(n0[0],n0[1],n1[0]);mb=max3f(n0[2],n0[3],n1[1]);PINAB();}while(0));
;   PVG(9,pw2,vfb,13,0.f,0.f,0.f,0.f, do{ma=max3f(ma,n1[2],n1[3]);mb=max3f(mb,n0[4],n0[5]);PINAB();}while(0));
;   PVG(10,pw2,vfc,14,0.f,0.f,0.f,0.f, do{ma=max3f(ma,n0[6],n0[7]);mb=max3f(mb,n1[4],n1[5]);PINAB();}while(0));
;   PVG(11,pw2,vfd,15,0.f,0.f,0.f,0.f, do{ma=max3f(ma,n1[6],n1[7]);mb=max3f(mb,n0[8],n0[9]);PINAB();}while(0));
;   PVG(12,pw3,vfa,16,0.f,0.f,0.f,0.f, do{ma=max3f(ma,n0[10],n0[11]);mb=max3f(mb,n1[8],n1[9]);PINAB();}while(0));
;   PVG(13,pw3,vfb,16,0.f,0.f,0.f,0.f, do{ma=max3f(ma,n1[10],n1[11]);mb=max3f(mb,n0[12],n0[13]);PINAB();}while(0));
;   PVG(14,pw3,vfc,16,0.f,0.f,0.f,0.f, do{ma=max3f(ma,n0[14],n0[15]);mb=max3f(mb,n1[12],n1[13]);PINAB();}while(0));
;   PVG(15,pw3,vfd,16,0.f,0.f,0.f,0.f, do{ma=max3f(ma,n1[14],n1[15]);ma=max2f(ma,mb);PINAB();}while(0));
;     ...
;   { auto rr=__builtin_amdgcn_permlane32_swap(__float_as_uint(ma),__float_as_uint(ma),false,false); rm=max2f(__uint_as_float(rr[0]),__uint_as_float(rr[1])); }
;     ...
;   S.l_reg+=sa;
	v_mfma_f32_32x32x16_bf16 v[18:33], v[82:85], v[12:15], v[18:33]
	ds_read_b64_tr_b16 v[8:9], v246 offset:26624
	ds_read_b64_tr_b16 v[10:11], v246 offset:27136
	ds_read_b128 v[220:223], v240 offset:4096
	v_add_f32_e32 v17, v182, v17
	v_add_f32_e32 v17, v183, v17
	v_add_f32_e32 v17, v184, v17
	v_add_f32_e32 v17, v185, v17
	v_cvt_pk_bf16_f32 v12, v180, v181
	v_cvt_pk_bf16_f32 v13, v182, v183
	v_cvt_pk_bf16_f32 v14, v184, v185
	v_cvt_pk_bf16_f32 v15, v186, v187
	s_waitcnt lgkmcnt(10)
	v_mfma_f32_32x32x16_bf16 v[34:49], v[82:85], v[4:7], v[34:49]
	ds_read_b64_tr_b16 v[94:95], v246 offset:30720
	ds_read_b64_tr_b16 v[96:97], v246 offset:31232
	ds_read_b128 v[224:227], v240 offset:4608
	v_add_f32_e32 v17, v186, v17
	v_add_f32_e32 v17, v187, v17
	v_add_f32_e32 v17, v102, v17
	v_add_f32_e32 v17, v103, v17
	v_cvt_pk_bf16_f32 v4, v102, v103
	v_cvt_pk_bf16_f32 v5, v104, v105
	v_cvt_pk_bf16_f32 v6, v106, v107
	v_cvt_pk_bf16_f32 v7, v108, v109
	s_waitcnt lgkmcnt(10)
	v_mfma_f32_32x32x16_bf16 v[50:65], v[82:85], v[86:89], v[50:65]
	ds_read_b64_tr_b16 v[98:99], v246 offset:34816
	ds_read_b64_tr_b16 v[100:101], v246 offset:35328
	ds_read_b128 v[228:231], v240 offset:6144
	v_add_f32_e32 v17, v104, v17
	v_add_f32_e32 v17, v105, v17
	v_add_f32_e32 v17, v106, v17
	v_add_f32_e32 v17, v107, v17
	s_waitcnt lgkmcnt(10)
	v_mfma_f32_32x32x16_bf16 v[66:81], v[82:85], v[90:93], v[66:81]
	ds_read_b64_tr_b16 v[86:87], v246 offset:38912
	ds_read_b64_tr_b16 v[88:89], v246 offset:39424
	ds_read_b128 v[232:235], v240 offset:6656
	v_add_f32_e32 v17, v108, v17
	v_add_f32_e32 v17, v109, v17
	v_add_f32_e32 v17, 0, v17
	s_waitcnt lgkmcnt(10)
	v_mfma_f32_32x32x16_bf16 v[18:33], v[12:15], v[8:11], v[18:33]
	ds_read_b64_tr_b16 v[82:83], v246 offset:27648
	ds_read_b64_tr_b16 v[84:85], v246 offset:28160
	v_max3_f32 v90, v130, v131, v114
	v_max3_f32 v91, v132, v133, v115
	s_nop 0
	s_waitcnt lgkmcnt(9)
	v_mfma_f32_32x32x16_bf16 v[34:49], v[12:15], v[94:97], v[34:49]
	ds_read_b64_tr_b16 v[8:9], v246 offset:31744
	ds_read_b64_tr_b16 v[10:11], v246 offset:32256
	v_max3_f32 v102, v90, v116, v117
	v_max3_f32 v103, v91, v134, v135
	s_nop 0
	s_waitcnt lgkmcnt(8)
	v_mfma_f32_32x32x16_bf16 v[50:65], v[12:15], v[98:101], v[50:65]
	ds_read_b64_tr_b16 v[90:91], v246 offset:35840
	ds_read_b64_tr_b16 v[92:93], v246 offset:36352
	v_max3_f32 v102, v102, v136, v137
	v_max3_f32 v103, v103, v118, v119
	s_nop 0
	s_waitcnt lgkmcnt(7)
	v_mfma_f32_32x32x16_bf16 v[66:81], v[12:15], v[86:89], v[66:81]
	ds_read_b64_tr_b16 v[94:95], v246 offset:39936
	ds_read_b64_tr_b16 v[96:97], v246 offset:40448
	v_max3_f32 v98, v102, v120, v121
	v_max3_f32 v99, v103, v138, v139
	s_nop 0
	s_waitcnt lgkmcnt(6)
	v_mfma_f32_32x32x16_bf16 v[18:33], v[4:7], v[82:85], v[18:33]
	v_max3_f32 v12, v98, v140, v141
	v_max3_f32 v13, v99, v122, v123
	s_nop 0
	s_waitcnt lgkmcnt(4)
	v_mfma_f32_32x32x16_bf16 v[34:49], v[4:7], v[8:11], v[34:49]
	v_max3_f32 v12, v12, v124, v125
	v_max3_f32 v13, v13, v142, v143
	s_nop 0
	s_waitcnt lgkmcnt(2)
	v_mfma_f32_32x32x16_bf16 v[50:65], v[4:7], v[90:93], v[50:65]
	v_max3_f32 v8, v12, v144, v145
	v_max3_f32 v9, v13, v126, v127
	s_nop 0
	s_waitcnt lgkmcnt(0)
	v_mfma_f32_32x32x16_bf16 v[66:81], v[4:7], v[94:97], v[66:81]
	v_max3_f32 v8, v8, v128, v129
	s_nop 0
	v_max_f32_e32 v8, v8, v9
	s_nop 0
	v_mov_b32_e32 v162, v8
	v_mov_b32_e32 v163, v8
	s_waitcnt vmcnt(0) lgkmcnt(0)
	s_barrier
	v_permlane32_swap_b32_e32 v162, v163
	v_max_f32_e32 v94, v162, v163
	v_add_f32_e32 v17, v251, v17
	v_cmp_lt_f32_e32 vcc, s67, v94
	s_cbranch_vccz .LBB0_435
	v_max_f32_e32 v94, v94, v94
	v_max_f32_e32 v94, 0, v94
	v_exp_f32_e64 v95, -v94
	s_and_saveexec_b64 s[58:59], s[6:7]
	s_cbranch_execz .LBB0_434
	ds_write_b32 v16, v95
	s_branch .LBB0_434
